# XCD-local seams, 2 stagger groups (XCDs 4-7 start P4 ~12us late); P4/P6' epilogue rewrites
# speedup vs baseline: 1.0069x; 1.0004x over previous
.LBB0_392:
	s_or_b64 exec, exec, s[0:1]
	v_mov_b32_e32 v0, 0
	s_add_u32 s98, s66, 0x40000
	s_addc_u32 s99, s67, 0
	s_nop 0
	global_load_dwordx4 v[4:7], v0, s[98:99] offset:32 sc1
	global_load_dwordx4 v[8:11], v0, s[98:99] offset:48 sc1
	s_mov_b32 s100, 1
	s_waitcnt vmcnt(0)
	v_readfirstlane_b32 s101, v4
	s_bcnt1_i32_b32 s101, s101
	s_cmp_eq_u32 s101, 1
	s_cselect_b32 s100, s100, 0
	v_readfirstlane_b32 s101, v5
	s_bcnt1_i32_b32 s101, s101
	s_cmp_eq_u32 s101, 1
	s_cselect_b32 s100, s100, 0
	v_readfirstlane_b32 s101, v6
	s_bcnt1_i32_b32 s101, s101
	s_cmp_eq_u32 s101, 1
	s_cselect_b32 s100, s100, 0
	v_readfirstlane_b32 s101, v7
	s_bcnt1_i32_b32 s101, s101
	s_cmp_eq_u32 s101, 1
	s_cselect_b32 s100, s100, 0
	v_readfirstlane_b32 s101, v8
	s_bcnt1_i32_b32 s101, s101
	s_cmp_eq_u32 s101, 1
	s_cselect_b32 s100, s100, 0
	v_readfirstlane_b32 s101, v9
	s_bcnt1_i32_b32 s101, s101
	s_cmp_eq_u32 s101, 1
	s_cselect_b32 s100, s100, 0
	v_readfirstlane_b32 s101, v10
	s_bcnt1_i32_b32 s101, s101
	s_cmp_eq_u32 s101, 1
	s_cselect_b32 s100, s100, 0
	v_readfirstlane_b32 s101, v11
	s_bcnt1_i32_b32 s101, s101
	s_cmp_eq_u32 s101, 1
	s_cselect_b32 s100, s100, 0
	v_writelane_b32 v255, s100, 0
	s_cmp_eq_u32 s100, 0
	s_cbranch_scc1 .Lxl_stag_done
	v_readlane_b32 s101, v254, 0
	s_nop 3
	s_lshr_b32 s101, s101, 2
	s_cmp_eq_u32 s101, 0
	s_cbranch_scc1 .Lxl_stag_done
.Lxl_stag_loop:
	s_sleep 127
	s_sleep 127
	s_sleep 127
	s_sleep 3
	s_add_i32 s101, s101, -1
	s_cmp_lg_u32 s101, 0
	s_cbranch_scc1 .Lxl_stag_loop
